# one s_barrier per MFMA block (leading half syncs after its MFMAs, trailing half after its loads), leading half's vmcnt wait moved after its MFMA block, trailing half MFMAs at prio 2
# baseline (speedup 1.0000x reference)
.LBB0_169:
	s_add_u32 s34, s50, 0xfff80080
	s_addc_u32 s35, s51, -1
	s_add_i32 s52, 0, 0x10000
	s_cmp_eq_u32 s77, 28
	s_cselect_b32 s55, s36, s35
	s_cselect_b32 s54, s37, s34
	v_add_u32_e32 v145, s52, v142
	s_cselect_b32 s35, s41, s76
	s_cselect_b32 s34, s43, s71
	s_add_i32 s53, 0, 0x14000
	ds_read_b128 v[146:149], v145
	ds_read_b128 v[150:153], v145 offset:1024
	ds_read_b128 v[172:175], v145 offset:2048
	ds_read_b128 v[176:179], v145 offset:3072
	v_add_u32_e32 v145, s53, v142
	ds_read_b128 v[180:183], v145
	ds_read_b128 v[184:187], v145 offset:1024
	ds_read_b128 v[188:191], v145 offset:2048
	ds_read_b128 v[192:195], v145 offset:3072
	v_lshl_add_u64 v[154:155], s[50:51], 0, v[138:139]
	s_add_i32 m0, s57, 0xc000
	ds_read_b128 v[196:199], v144
	ds_read_b128 v[200:203], v144 offset:1024
	ds_read_b128 v[204:207], v144 offset:2048
	ds_read_b128 v[208:211], v144 offset:3072
	ds_read_b128 v[212:215], v144 offset:4096
	ds_read_b128 v[216:219], v144 offset:5120
	ds_read_b128 v[228:231], v144 offset:6144
	ds_read_b128 v[232:235], v144 offset:7168
	global_load_lds_dwordx4 v[154:155], off
	v_lshl_add_u64 v[154:155], s[50:51], 0, v[140:141]
	s_add_i32 m0, s57, 0xe000
	s_nop 0
	global_load_lds_dwordx4 v[154:155], off
	s_waitcnt lgkmcnt(0)
	s_cmp_eq_u32 s101, 0
	s_cbranch_scc1 .LtypeA_0
	s_waitcnt vmcnt(8)
	s_barrier
	s_setprio 2
	v_mfma_f32_16x16x32_bf16 v[128:131], v[146:149], v[196:199], v[128:131]
	v_mfma_f32_16x16x32_bf16 v[128:131], v[150:153], v[200:203], v[128:131]
	v_mfma_f32_16x16x32_bf16 v[124:127], v[172:175], v[196:199], v[124:127]
	v_mfma_f32_16x16x32_bf16 v[124:127], v[176:179], v[200:203], v[124:127]
	v_mfma_f32_16x16x32_bf16 v[108:111], v[172:175], v[204:207], v[108:111]
	v_mfma_f32_16x16x32_bf16 v[108:111], v[176:179], v[208:211], v[108:111]
	v_mfma_f32_16x16x32_bf16 v[112:115], v[146:149], v[204:207], v[112:115]
	v_mfma_f32_16x16x32_bf16 v[112:115], v[150:153], v[208:211], v[112:115]
	v_mfma_f32_16x16x32_bf16 v[96:99], v[146:149], v[212:215], v[96:99]
	v_mfma_f32_16x16x32_bf16 v[96:99], v[150:153], v[216:219], v[96:99]
	v_mfma_f32_16x16x32_bf16 v[92:95], v[172:175], v[212:215], v[92:95]
	v_mfma_f32_16x16x32_bf16 v[92:95], v[176:179], v[216:219], v[92:95]
	v_mfma_f32_16x16x32_bf16 v[76:79], v[172:175], v[228:231], v[76:79]
	v_mfma_f32_16x16x32_bf16 v[76:79], v[176:179], v[232:235], v[76:79]
	v_mfma_f32_16x16x32_bf16 v[80:83], v[146:149], v[228:231], v[80:83]
	v_mfma_f32_16x16x32_bf16 v[80:83], v[150:153], v[232:235], v[80:83]
	v_mfma_f32_16x16x32_bf16 v[120:123], v[180:183], v[196:199], v[120:123]
	v_mfma_f32_16x16x32_bf16 v[120:123], v[184:187], v[200:203], v[120:123]
	v_mfma_f32_16x16x32_bf16 v[116:119], v[188:191], v[196:199], v[116:119]
	v_mfma_f32_16x16x32_bf16 v[116:119], v[192:195], v[200:203], v[116:119]
	v_mfma_f32_16x16x32_bf16 v[100:103], v[188:191], v[204:207], v[100:103]
	v_mfma_f32_16x16x32_bf16 v[100:103], v[192:195], v[208:211], v[100:103]
	v_mfma_f32_16x16x32_bf16 v[104:107], v[180:183], v[204:207], v[104:107]
	v_mfma_f32_16x16x32_bf16 v[104:107], v[184:187], v[208:211], v[104:107]
	v_mfma_f32_16x16x32_bf16 v[88:91], v[180:183], v[212:215], v[88:91]
	v_mfma_f32_16x16x32_bf16 v[88:91], v[184:187], v[216:219], v[88:91]
	v_mfma_f32_16x16x32_bf16 v[84:87], v[188:191], v[212:215], v[84:87]
	v_mfma_f32_16x16x32_bf16 v[84:87], v[192:195], v[216:219], v[84:87]
	v_mfma_f32_16x16x32_bf16 v[68:71], v[188:191], v[228:231], v[68:71]
	v_mfma_f32_16x16x32_bf16 v[68:71], v[192:195], v[232:235], v[68:71]
	v_mfma_f32_16x16x32_bf16 v[72:75], v[180:183], v[228:231], v[72:75]
	v_mfma_f32_16x16x32_bf16 v[72:75], v[184:187], v[232:235], v[72:75]
	s_branch .Ljoin_0
.LtypeA_0:
	s_setprio 1
	v_mfma_f32_16x16x32_bf16 v[128:131], v[146:149], v[196:199], v[128:131]
	v_mfma_f32_16x16x32_bf16 v[128:131], v[150:153], v[200:203], v[128:131]
	v_mfma_f32_16x16x32_bf16 v[124:127], v[172:175], v[196:199], v[124:127]
	v_mfma_f32_16x16x32_bf16 v[124:127], v[176:179], v[200:203], v[124:127]
	v_mfma_f32_16x16x32_bf16 v[108:111], v[172:175], v[204:207], v[108:111]
	v_mfma_f32_16x16x32_bf16 v[108:111], v[176:179], v[208:211], v[108:111]
	v_mfma_f32_16x16x32_bf16 v[112:115], v[146:149], v[204:207], v[112:115]
	v_mfma_f32_16x16x32_bf16 v[112:115], v[150:153], v[208:211], v[112:115]
	v_mfma_f32_16x16x32_bf16 v[96:99], v[146:149], v[212:215], v[96:99]
	v_mfma_f32_16x16x32_bf16 v[96:99], v[150:153], v[216:219], v[96:99]
	v_mfma_f32_16x16x32_bf16 v[92:95], v[172:175], v[212:215], v[92:95]
	v_mfma_f32_16x16x32_bf16 v[92:95], v[176:179], v[216:219], v[92:95]
	v_mfma_f32_16x16x32_bf16 v[76:79], v[172:175], v[228:231], v[76:79]
	v_mfma_f32_16x16x32_bf16 v[76:79], v[176:179], v[232:235], v[76:79]
	v_mfma_f32_16x16x32_bf16 v[80:83], v[146:149], v[228:231], v[80:83]
	v_mfma_f32_16x16x32_bf16 v[80:83], v[150:153], v[232:235], v[80:83]
	v_mfma_f32_16x16x32_bf16 v[120:123], v[180:183], v[196:199], v[120:123]
	v_mfma_f32_16x16x32_bf16 v[120:123], v[184:187], v[200:203], v[120:123]
	v_mfma_f32_16x16x32_bf16 v[116:119], v[188:191], v[196:199], v[116:119]
	v_mfma_f32_16x16x32_bf16 v[116:119], v[192:195], v[200:203], v[116:119]
	v_mfma_f32_16x16x32_bf16 v[100:103], v[188:191], v[204:207], v[100:103]
	v_mfma_f32_16x16x32_bf16 v[100:103], v[192:195], v[208:211], v[100:103]
	v_mfma_f32_16x16x32_bf16 v[104:107], v[180:183], v[204:207], v[104:107]
	v_mfma_f32_16x16x32_bf16 v[104:107], v[184:187], v[208:211], v[104:107]
	v_mfma_f32_16x16x32_bf16 v[88:91], v[180:183], v[212:215], v[88:91]
	v_mfma_f32_16x16x32_bf16 v[88:91], v[184:187], v[216:219], v[88:91]
	v_mfma_f32_16x16x32_bf16 v[84:87], v[188:191], v[212:215], v[84:87]
	v_mfma_f32_16x16x32_bf16 v[84:87], v[192:195], v[216:219], v[84:87]
	v_mfma_f32_16x16x32_bf16 v[68:71], v[188:191], v[228:231], v[68:71]
	v_mfma_f32_16x16x32_bf16 v[68:71], v[192:195], v[232:235], v[68:71]
	v_mfma_f32_16x16x32_bf16 v[72:75], v[180:183], v[228:231], v[72:75]
	v_mfma_f32_16x16x32_bf16 v[72:75], v[184:187], v[232:235], v[72:75]
	s_waitcnt vmcnt(8)
	s_setprio 0
	s_barrier
.Ljoin_0:
	s_add_i32 s52, s52, s19
	v_lshl_add_u64 v[154:155], s[34:35], 0, v[134:135]
	s_mov_b32 m0, s52
	ds_read_b128 v[196:199], v144 offset:16384
	ds_read_b128 v[200:203], v144 offset:17408
	ds_read_b128 v[204:207], v144 offset:18432
	ds_read_b128 v[208:211], v144 offset:19456
	ds_read_b128 v[212:215], v144 offset:20480
	ds_read_b128 v[216:219], v144 offset:21504
	ds_read_b128 v[228:231], v144 offset:22528
	ds_read_b128 v[232:235], v144 offset:23552
	global_load_lds_dwordx4 v[154:155], off
	s_add_i32 m0, s52, 0x2000
	s_add_u32 s96, s34, 0x4000
	v_lshl_add_u64 v[154:155], s[34:35], 0, v[0:1]
	s_addc_u32 s97, s35, 0
	s_add_i32 s52, s53, s19
	global_load_lds_dwordx4 v[154:155], off
	v_lshl_add_u64 v[154:155], s[96:97], 0, v[134:135]
	s_mov_b32 m0, s52
	v_lshl_add_u64 v[236:237], s[54:55], 0, v[132:133]
	global_load_lds_dwordx4 v[154:155], off
	v_lshl_add_u64 v[154:155], s[96:97], 0, v[0:1]
	s_add_i32 m0, s52, 0x2000
	s_nop 0
	global_load_lds_dwordx4 v[154:155], off
	v_lshl_add_u64 v[154:155], s[54:55], 0, v[136:137]
	s_mov_b32 m0, s57
	s_nop 0
	global_load_lds_dwordx4 v[154:155], off
	s_mov_b32 m0, s58
	s_nop 0
	global_load_lds_dwordx4 v[236:237], off
	s_waitcnt lgkmcnt(0)
	s_cmp_eq_u32 s101, 0
	s_cbranch_scc1 .LtypeA_1
	s_waitcnt vmcnt(8)
	s_barrier
	s_setprio 2
	v_mfma_f32_16x16x32_bf16 v[64:67], v[146:149], v[196:199], v[64:67]
	v_mfma_f32_16x16x32_bf16 v[64:67], v[150:153], v[200:203], v[64:67]
	v_mfma_f32_16x16x32_bf16 v[60:63], v[172:175], v[196:199], v[60:63]
	v_mfma_f32_16x16x32_bf16 v[60:63], v[176:179], v[200:203], v[60:63]
	v_mfma_f32_16x16x32_bf16 v[44:47], v[172:175], v[204:207], v[44:47]
	v_mfma_f32_16x16x32_bf16 v[44:47], v[176:179], v[208:211], v[44:47]
	v_mfma_f32_16x16x32_bf16 v[48:51], v[146:149], v[204:207], v[48:51]
	v_mfma_f32_16x16x32_bf16 v[48:51], v[150:153], v[208:211], v[48:51]
	v_mfma_f32_16x16x32_bf16 v[32:35], v[146:149], v[212:215], v[32:35]
	v_mfma_f32_16x16x32_bf16 v[32:35], v[150:153], v[216:219], v[32:35]
	v_mfma_f32_16x16x32_bf16 v[28:31], v[172:175], v[212:215], v[28:31]
	v_mfma_f32_16x16x32_bf16 v[28:31], v[176:179], v[216:219], v[28:31]
	v_mfma_f32_16x16x32_bf16 v[12:15], v[172:175], v[228:231], v[12:15]
	v_mfma_f32_16x16x32_bf16 v[12:15], v[176:179], v[232:235], v[12:15]
	v_mfma_f32_16x16x32_bf16 v[16:19], v[146:149], v[228:231], v[16:19]
	v_mfma_f32_16x16x32_bf16 v[16:19], v[150:153], v[232:235], v[16:19]
	v_mfma_f32_16x16x32_bf16 v[56:59], v[180:183], v[196:199], v[56:59]
	v_mfma_f32_16x16x32_bf16 v[56:59], v[184:187], v[200:203], v[56:59]
	v_mfma_f32_16x16x32_bf16 v[52:55], v[188:191], v[196:199], v[52:55]
	v_mfma_f32_16x16x32_bf16 v[52:55], v[192:195], v[200:203], v[52:55]
	v_mfma_f32_16x16x32_bf16 v[36:39], v[188:191], v[204:207], v[36:39]
	v_mfma_f32_16x16x32_bf16 v[36:39], v[192:195], v[208:211], v[36:39]
	v_mfma_f32_16x16x32_bf16 v[40:43], v[180:183], v[204:207], v[40:43]
	v_mfma_f32_16x16x32_bf16 v[40:43], v[184:187], v[208:211], v[40:43]
	v_mfma_f32_16x16x32_bf16 v[24:27], v[180:183], v[212:215], v[24:27]
	v_mfma_f32_16x16x32_bf16 v[24:27], v[184:187], v[216:219], v[24:27]
	v_mfma_f32_16x16x32_bf16 v[20:23], v[188:191], v[212:215], v[20:23]
	v_mfma_f32_16x16x32_bf16 v[20:23], v[192:195], v[216:219], v[20:23]
	v_mfma_f32_16x16x32_bf16 v[4:7], v[188:191], v[228:231], v[4:7]
	v_mfma_f32_16x16x32_bf16 v[4:7], v[192:195], v[232:235], v[4:7]
	v_mfma_f32_16x16x32_bf16 v[8:11], v[180:183], v[228:231], v[8:11]
	v_mfma_f32_16x16x32_bf16 v[8:11], v[184:187], v[232:235], v[8:11]
	s_branch .Ljoin_1
.LtypeA_1:
	s_setprio 1
	v_mfma_f32_16x16x32_bf16 v[64:67], v[146:149], v[196:199], v[64:67]
	v_mfma_f32_16x16x32_bf16 v[64:67], v[150:153], v[200:203], v[64:67]
	v_mfma_f32_16x16x32_bf16 v[60:63], v[172:175], v[196:199], v[60:63]
	v_mfma_f32_16x16x32_bf16 v[60:63], v[176:179], v[200:203], v[60:63]
	v_mfma_f32_16x16x32_bf16 v[44:47], v[172:175], v[204:207], v[44:47]
	v_mfma_f32_16x16x32_bf16 v[44:47], v[176:179], v[208:211], v[44:47]
	v_mfma_f32_16x16x32_bf16 v[48:51], v[146:149], v[204:207], v[48:51]
	v_mfma_f32_16x16x32_bf16 v[48:51], v[150:153], v[208:211], v[48:51]
	v_mfma_f32_16x16x32_bf16 v[32:35], v[146:149], v[212:215], v[32:35]
	v_mfma_f32_16x16x32_bf16 v[32:35], v[150:153], v[216:219], v[32:35]
	v_mfma_f32_16x16x32_bf16 v[28:31], v[172:175], v[212:215], v[28:31]
	v_mfma_f32_16x16x32_bf16 v[28:31], v[176:179], v[216:219], v[28:31]
	v_mfma_f32_16x16x32_bf16 v[12:15], v[172:175], v[228:231], v[12:15]
	v_mfma_f32_16x16x32_bf16 v[12:15], v[176:179], v[232:235], v[12:15]
	v_mfma_f32_16x16x32_bf16 v[16:19], v[146:149], v[228:231], v[16:19]
	v_mfma_f32_16x16x32_bf16 v[16:19], v[150:153], v[232:235], v[16:19]
	v_mfma_f32_16x16x32_bf16 v[56:59], v[180:183], v[196:199], v[56:59]
	v_mfma_f32_16x16x32_bf16 v[56:59], v[184:187], v[200:203], v[56:59]
	v_mfma_f32_16x16x32_bf16 v[52:55], v[188:191], v[196:199], v[52:55]
	v_mfma_f32_16x16x32_bf16 v[52:55], v[192:195], v[200:203], v[52:55]
	v_mfma_f32_16x16x32_bf16 v[36:39], v[188:191], v[204:207], v[36:39]
	v_mfma_f32_16x16x32_bf16 v[36:39], v[192:195], v[208:211], v[36:39]
	v_mfma_f32_16x16x32_bf16 v[40:43], v[180:183], v[204:207], v[40:43]
	v_mfma_f32_16x16x32_bf16 v[40:43], v[184:187], v[208:211], v[40:43]
	v_mfma_f32_16x16x32_bf16 v[24:27], v[180:183], v[212:215], v[24:27]
	v_mfma_f32_16x16x32_bf16 v[24:27], v[184:187], v[216:219], v[24:27]
	v_mfma_f32_16x16x32_bf16 v[20:23], v[188:191], v[212:215], v[20:23]
	v_mfma_f32_16x16x32_bf16 v[20:23], v[192:195], v[216:219], v[20:23]
	v_mfma_f32_16x16x32_bf16 v[4:7], v[188:191], v[228:231], v[4:7]
	v_mfma_f32_16x16x32_bf16 v[4:7], v[192:195], v[232:235], v[4:7]
	v_mfma_f32_16x16x32_bf16 v[8:11], v[180:183], v[228:231], v[8:11]
	v_mfma_f32_16x16x32_bf16 v[8:11], v[184:187], v[232:235], v[8:11]
	s_waitcnt vmcnt(8)
	s_setprio 0
	s_barrier
.Ljoin_1:
	s_add_i32 s52, 0, 0x18000
	v_add_u32_e32 v145, s52, v142
	s_add_i32 s53, 0, 0x1c000
	ds_read_b128 v[146:149], v145
	ds_read_b128 v[150:153], v145 offset:1024
	ds_read_b128 v[172:175], v145 offset:2048
	ds_read_b128 v[176:179], v145 offset:3072
	v_add_u32_e32 v145, s53, v142
	ds_read_b128 v[180:183], v145
	ds_read_b128 v[184:187], v145 offset:1024
	ds_read_b128 v[188:191], v145 offset:2048
	ds_read_b128 v[192:195], v145 offset:3072
	s_add_u32 s54, s54, 0x80000
	s_addc_u32 s55, s55, 0
	s_mov_b32 m0, s59
	v_lshl_add_u64 v[238:239], s[54:55], 0, v[136:137]
	ds_read_b128 v[196:199], v144 offset:32768
	ds_read_b128 v[200:203], v144 offset:33792
	ds_read_b128 v[204:207], v144 offset:34816
	ds_read_b128 v[208:211], v144 offset:35840
	ds_read_b128 v[212:215], v144 offset:36864
	ds_read_b128 v[216:219], v144 offset:37888
	ds_read_b128 v[228:231], v144 offset:38912
	ds_read_b128 v[232:235], v144 offset:39936
	global_load_lds_dwordx4 v[238:239], off
	v_lshl_add_u64 v[238:239], s[54:55], 0, v[132:133]
	s_mov_b32 m0, s60
	s_nop 0
	global_load_lds_dwordx4 v[238:239], off
	s_waitcnt lgkmcnt(0)
	s_cmp_eq_u32 s101, 0
	s_cbranch_scc1 .LtypeA_2
	s_waitcnt vmcnt(8)
	s_barrier
	s_setprio 2
	v_mfma_f32_16x16x32_bf16 v[128:131], v[146:149], v[196:199], v[128:131]
	v_mfma_f32_16x16x32_bf16 v[128:131], v[150:153], v[200:203], v[128:131]
	v_mfma_f32_16x16x32_bf16 v[124:127], v[172:175], v[196:199], v[124:127]
	v_mfma_f32_16x16x32_bf16 v[124:127], v[176:179], v[200:203], v[124:127]
	v_mfma_f32_16x16x32_bf16 v[108:111], v[172:175], v[204:207], v[108:111]
	v_mfma_f32_16x16x32_bf16 v[108:111], v[176:179], v[208:211], v[108:111]
	v_mfma_f32_16x16x32_bf16 v[112:115], v[146:149], v[204:207], v[112:115]
	v_mfma_f32_16x16x32_bf16 v[112:115], v[150:153], v[208:211], v[112:115]
	v_mfma_f32_16x16x32_bf16 v[96:99], v[146:149], v[212:215], v[96:99]
	v_mfma_f32_16x16x32_bf16 v[96:99], v[150:153], v[216:219], v[96:99]
	v_mfma_f32_16x16x32_bf16 v[92:95], v[172:175], v[212:215], v[92:95]
	v_mfma_f32_16x16x32_bf16 v[92:95], v[176:179], v[216:219], v[92:95]
	v_mfma_f32_16x16x32_bf16 v[76:79], v[172:175], v[228:231], v[76:79]
	v_mfma_f32_16x16x32_bf16 v[76:79], v[176:179], v[232:235], v[76:79]
	v_mfma_f32_16x16x32_bf16 v[80:83], v[146:149], v[228:231], v[80:83]
	v_mfma_f32_16x16x32_bf16 v[80:83], v[150:153], v[232:235], v[80:83]
	v_mfma_f32_16x16x32_bf16 v[120:123], v[180:183], v[196:199], v[120:123]
	v_mfma_f32_16x16x32_bf16 v[120:123], v[184:187], v[200:203], v[120:123]
	v_mfma_f32_16x16x32_bf16 v[116:119], v[188:191], v[196:199], v[116:119]
	v_mfma_f32_16x16x32_bf16 v[116:119], v[192:195], v[200:203], v[116:119]
	v_mfma_f32_16x16x32_bf16 v[100:103], v[188:191], v[204:207], v[100:103]
	v_mfma_f32_16x16x32_bf16 v[100:103], v[192:195], v[208:211], v[100:103]
	v_mfma_f32_16x16x32_bf16 v[104:107], v[180:183], v[204:207], v[104:107]
	v_mfma_f32_16x16x32_bf16 v[104:107], v[184:187], v[208:211], v[104:107]
	v_mfma_f32_16x16x32_bf16 v[88:91], v[180:183], v[212:215], v[88:91]
	v_mfma_f32_16x16x32_bf16 v[88:91], v[184:187], v[216:219], v[88:91]
	v_mfma_f32_16x16x32_bf16 v[84:87], v[188:191], v[212:215], v[84:87]
	v_mfma_f32_16x16x32_bf16 v[84:87], v[192:195], v[216:219], v[84:87]
	v_mfma_f32_16x16x32_bf16 v[68:71], v[188:191], v[228:231], v[68:71]
	v_mfma_f32_16x16x32_bf16 v[68:71], v[192:195], v[232:235], v[68:71]
	v_mfma_f32_16x16x32_bf16 v[72:75], v[180:183], v[228:231], v[72:75]
	v_mfma_f32_16x16x32_bf16 v[72:75], v[184:187], v[232:235], v[72:75]
	s_branch .Ljoin_2

.Ljoin_2:
	s_add_u32 s54, s34, 0x160000
	s_addc_u32 s55, s35, 0
	s_add_i32 s52, s52, s19
	v_lshl_add_u64 v[238:239], s[54:55], 0, v[134:135]
	s_mov_b32 m0, s52
	ds_read_b128 v[196:199], v144 offset:49152
	ds_read_b128 v[200:203], v144 offset:50176
	ds_read_b128 v[204:207], v144 offset:51200
	ds_read_b128 v[208:211], v144 offset:52224
	ds_read_b128 v[212:215], v144 offset:53248
	ds_read_b128 v[216:219], v144 offset:54272
	ds_read_b128 v[228:231], v144 offset:55296
	ds_read_b128 v[232:235], v144 offset:56320
	global_load_lds_dwordx4 v[238:239], off
	s_add_i32 m0, s52, 0x2000
	s_add_u32 s34, s34, 0x164000
	v_lshl_add_u64 v[238:239], s[54:55], 0, v[0:1]
	s_addc_u32 s35, s35, 0
	s_add_i32 s52, s53, s19
	global_load_lds_dwordx4 v[238:239], off
	v_lshl_add_u64 v[238:239], s[34:35], 0, v[134:135]
	s_mov_b32 m0, s52
	v_lshl_add_u64 v[154:155], v[154:155], 0, s[14:15]
	global_load_lds_dwordx4 v[238:239], off
	v_lshl_add_u64 v[238:239], s[34:35], 0, v[0:1]
	s_add_i32 m0, s52, 0x2000
	s_nop 0
	global_load_lds_dwordx4 v[238:239], off
	s_mov_b32 m0, s61
	s_nop 0
	global_load_lds_dwordx4 v[154:155], off
	v_lshl_add_u64 v[154:155], v[236:237], 0, s[14:15]
	s_mov_b32 m0, s62
	s_nop 0
	global_load_lds_dwordx4 v[154:155], off
	s_waitcnt lgkmcnt(0)
	s_cmp_eq_u32 s101, 0
	s_cbranch_scc1 .LtypeA_3
	s_waitcnt vmcnt(8)
	s_barrier
	s_setprio 2
	v_mfma_f32_16x16x32_bf16 v[64:67], v[146:149], v[196:199], v[64:67]
	v_mfma_f32_16x16x32_bf16 v[64:67], v[150:153], v[200:203], v[64:67]
	v_mfma_f32_16x16x32_bf16 v[60:63], v[172:175], v[196:199], v[60:63]
	v_mfma_f32_16x16x32_bf16 v[60:63], v[176:179], v[200:203], v[60:63]
	v_mfma_f32_16x16x32_bf16 v[44:47], v[172:175], v[204:207], v[44:47]
	v_mfma_f32_16x16x32_bf16 v[44:47], v[176:179], v[208:211], v[44:47]
	v_mfma_f32_16x16x32_bf16 v[48:51], v[146:149], v[204:207], v[48:51]
	v_mfma_f32_16x16x32_bf16 v[48:51], v[150:153], v[208:211], v[48:51]
	v_mfma_f32_16x16x32_bf16 v[32:35], v[146:149], v[212:215], v[32:35]
	v_mfma_f32_16x16x32_bf16 v[32:35], v[150:153], v[216:219], v[32:35]
	v_mfma_f32_16x16x32_bf16 v[28:31], v[172:175], v[212:215], v[28:31]
	v_mfma_f32_16x16x32_bf16 v[28:31], v[176:179], v[216:219], v[28:31]
	v_mfma_f32_16x16x32_bf16 v[12:15], v[172:175], v[228:231], v[12:15]
	v_mfma_f32_16x16x32_bf16 v[12:15], v[176:179], v[232:235], v[12:15]
	v_mfma_f32_16x16x32_bf16 v[16:19], v[146:149], v[228:231], v[16:19]
	v_mfma_f32_16x16x32_bf16 v[16:19], v[150:153], v[232:235], v[16:19]
	v_mfma_f32_16x16x32_bf16 v[56:59], v[180:183], v[196:199], v[56:59]
	v_mfma_f32_16x16x32_bf16 v[56:59], v[184:187], v[200:203], v[56:59]
	v_mfma_f32_16x16x32_bf16 v[52:55], v[188:191], v[196:199], v[52:55]
	v_mfma_f32_16x16x32_bf16 v[52:55], v[192:195], v[200:203], v[52:55]
	v_mfma_f32_16x16x32_bf16 v[36:39], v[188:191], v[204:207], v[36:39]
	v_mfma_f32_16x16x32_bf16 v[36:39], v[192:195], v[208:211], v[36:39]
	v_mfma_f32_16x16x32_bf16 v[40:43], v[180:183], v[204:207], v[40:43]
	v_mfma_f32_16x16x32_bf16 v[40:43], v[184:187], v[208:211], v[40:43]
	v_mfma_f32_16x16x32_bf16 v[24:27], v[180:183], v[212:215], v[24:27]
	v_mfma_f32_16x16x32_bf16 v[24:27], v[184:187], v[216:219], v[24:27]
	v_mfma_f32_16x16x32_bf16 v[20:23], v[188:191], v[212:215], v[20:23]
	v_mfma_f32_16x16x32_bf16 v[20:23], v[192:195], v[216:219], v[20:23]
	v_mfma_f32_16x16x32_bf16 v[4:7], v[188:191], v[228:231], v[4:7]
	v_mfma_f32_16x16x32_bf16 v[4:7], v[192:195], v[232:235], v[4:7]
	v_mfma_f32_16x16x32_bf16 v[8:11], v[180:183], v[228:231], v[8:11]
	v_mfma_f32_16x16x32_bf16 v[8:11], v[184:187], v[232:235], v[8:11]
	s_branch .Ljoin_3

.LBB0_243:
	s_add_u32 s34, s44, 0xfff80080
	s_addc_u32 s35, s45, -1
	s_add_i32 s52, 0, 0x10000
	s_cmp_eq_u32 vcc_hi, 28
	s_cselect_b32 s47, s36, s35
	s_cselect_b32 s46, s37, s34
	s_cselect_b32 s35, s55, vcc_lo
	s_cselect_b32 s34, s57, s63
	s_add_i32 s68, 0, 0x14000
	v_add_u32_e32 v144, s52, v155
	v_add_u32_e32 v180, s68, v155
	ds_read_b128 v[132:135], v144
	ds_read_b128 v[136:139], v144 offset:1024
	ds_read_b128 v[140:143], v144 offset:2048
	ds_read_b128 v[144:147], v144 offset:3072
	ds_read_b128 v[176:179], v180
	ds_read_b128 v[182:185], v180 offset:1024
	ds_read_b128 v[186:189], v180 offset:2048
	ds_read_b128 v[190:193], v180 offset:3072
	v_lshl_add_u64 v[218:219], s[44:45], 0, v[172:173]
	s_add_i32 m0, s69, 0xc000
	ds_read_b128 v[194:197], v181
	ds_read_b128 v[198:201], v181 offset:1024
	ds_read_b128 v[202:205], v181 offset:2048
	ds_read_b128 v[206:209], v181 offset:3072
	ds_read_b128 v[210:213], v181 offset:4096
	ds_read_b128 v[214:217], v181 offset:5120
	ds_read_b128 v[228:231], v181 offset:6144
	ds_read_b128 v[232:235], v181 offset:7168
	global_load_lds_dwordx4 v[218:219], off
	v_lshl_add_u64 v[218:219], s[44:45], 0, v[174:175]
	s_add_i32 m0, s69, 0xe000
	s_nop 0
	global_load_lds_dwordx4 v[218:219], off
	s_waitcnt lgkmcnt(0)
	s_cmp_eq_u32 s101, 0
	s_cbranch_scc1 .LtypeA_4
	s_waitcnt vmcnt(8)
	s_barrier
	s_setprio 2
	v_mfma_f32_16x16x32_bf16 v[128:131], v[132:135], v[194:197], v[128:131]
	v_mfma_f32_16x16x32_bf16 v[128:131], v[136:139], v[198:201], v[128:131]
	v_mfma_f32_16x16x32_bf16 v[124:127], v[140:143], v[194:197], v[124:127]
	v_mfma_f32_16x16x32_bf16 v[124:127], v[144:147], v[198:201], v[124:127]
	v_mfma_f32_16x16x32_bf16 v[108:111], v[140:143], v[202:205], v[108:111]
	v_mfma_f32_16x16x32_bf16 v[108:111], v[144:147], v[206:209], v[108:111]
	v_mfma_f32_16x16x32_bf16 v[112:115], v[132:135], v[202:205], v[112:115]
	v_mfma_f32_16x16x32_bf16 v[112:115], v[136:139], v[206:209], v[112:115]
	v_mfma_f32_16x16x32_bf16 v[96:99], v[132:135], v[210:213], v[96:99]
	v_mfma_f32_16x16x32_bf16 v[96:99], v[136:139], v[214:217], v[96:99]
	v_mfma_f32_16x16x32_bf16 v[92:95], v[140:143], v[210:213], v[92:95]
	v_mfma_f32_16x16x32_bf16 v[92:95], v[144:147], v[214:217], v[92:95]
	v_mfma_f32_16x16x32_bf16 v[76:79], v[140:143], v[228:231], v[76:79]
	v_mfma_f32_16x16x32_bf16 v[76:79], v[144:147], v[232:235], v[76:79]
	v_mfma_f32_16x16x32_bf16 v[80:83], v[132:135], v[228:231], v[80:83]
	v_mfma_f32_16x16x32_bf16 v[80:83], v[136:139], v[232:235], v[80:83]
	v_mfma_f32_16x16x32_bf16 v[120:123], v[176:179], v[194:197], v[120:123]
	v_mfma_f32_16x16x32_bf16 v[120:123], v[182:185], v[198:201], v[120:123]
	v_mfma_f32_16x16x32_bf16 v[116:119], v[186:189], v[194:197], v[116:119]
	v_mfma_f32_16x16x32_bf16 v[116:119], v[190:193], v[198:201], v[116:119]
	v_mfma_f32_16x16x32_bf16 v[100:103], v[186:189], v[202:205], v[100:103]
	v_mfma_f32_16x16x32_bf16 v[100:103], v[190:193], v[206:209], v[100:103]
	v_mfma_f32_16x16x32_bf16 v[104:107], v[176:179], v[202:205], v[104:107]
	v_mfma_f32_16x16x32_bf16 v[104:107], v[182:185], v[206:209], v[104:107]
	v_mfma_f32_16x16x32_bf16 v[88:91], v[176:179], v[210:213], v[88:91]
	v_mfma_f32_16x16x32_bf16 v[88:91], v[182:185], v[214:217], v[88:91]
	v_mfma_f32_16x16x32_bf16 v[84:87], v[186:189], v[210:213], v[84:87]
	v_mfma_f32_16x16x32_bf16 v[84:87], v[190:193], v[214:217], v[84:87]
	v_mfma_f32_16x16x32_bf16 v[68:71], v[186:189], v[228:231], v[68:71]
	v_mfma_f32_16x16x32_bf16 v[68:71], v[190:193], v[232:235], v[68:71]
	v_mfma_f32_16x16x32_bf16 v[72:75], v[176:179], v[228:231], v[72:75]
	v_mfma_f32_16x16x32_bf16 v[72:75], v[182:185], v[232:235], v[72:75]
	s_branch .Ljoin_4
.LtypeA_4:
	s_setprio 1
	v_mfma_f32_16x16x32_bf16 v[128:131], v[132:135], v[194:197], v[128:131]
	v_mfma_f32_16x16x32_bf16 v[128:131], v[136:139], v[198:201], v[128:131]
	v_mfma_f32_16x16x32_bf16 v[124:127], v[140:143], v[194:197], v[124:127]
	v_mfma_f32_16x16x32_bf16 v[124:127], v[144:147], v[198:201], v[124:127]
	v_mfma_f32_16x16x32_bf16 v[108:111], v[140:143], v[202:205], v[108:111]
	v_mfma_f32_16x16x32_bf16 v[108:111], v[144:147], v[206:209], v[108:111]
	v_mfma_f32_16x16x32_bf16 v[112:115], v[132:135], v[202:205], v[112:115]
	v_mfma_f32_16x16x32_bf16 v[112:115], v[136:139], v[206:209], v[112:115]
	v_mfma_f32_16x16x32_bf16 v[96:99], v[132:135], v[210:213], v[96:99]
	v_mfma_f32_16x16x32_bf16 v[96:99], v[136:139], v[214:217], v[96:99]
	v_mfma_f32_16x16x32_bf16 v[92:95], v[140:143], v[210:213], v[92:95]
	v_mfma_f32_16x16x32_bf16 v[92:95], v[144:147], v[214:217], v[92:95]
	v_mfma_f32_16x16x32_bf16 v[76:79], v[140:143], v[228:231], v[76:79]
	v_mfma_f32_16x16x32_bf16 v[76:79], v[144:147], v[232:235], v[76:79]
	v_mfma_f32_16x16x32_bf16 v[80:83], v[132:135], v[228:231], v[80:83]
	v_mfma_f32_16x16x32_bf16 v[80:83], v[136:139], v[232:235], v[80:83]
	v_mfma_f32_16x16x32_bf16 v[120:123], v[176:179], v[194:197], v[120:123]
	v_mfma_f32_16x16x32_bf16 v[120:123], v[182:185], v[198:201], v[120:123]
	v_mfma_f32_16x16x32_bf16 v[116:119], v[186:189], v[194:197], v[116:119]
	v_mfma_f32_16x16x32_bf16 v[116:119], v[190:193], v[198:201], v[116:119]
	v_mfma_f32_16x16x32_bf16 v[100:103], v[186:189], v[202:205], v[100:103]
	v_mfma_f32_16x16x32_bf16 v[100:103], v[190:193], v[206:209], v[100:103]
	v_mfma_f32_16x16x32_bf16 v[104:107], v[176:179], v[202:205], v[104:107]
	v_mfma_f32_16x16x32_bf16 v[104:107], v[182:185], v[206:209], v[104:107]
	v_mfma_f32_16x16x32_bf16 v[88:91], v[176:179], v[210:213], v[88:91]
	v_mfma_f32_16x16x32_bf16 v[88:91], v[182:185], v[214:217], v[88:91]
	v_mfma_f32_16x16x32_bf16 v[84:87], v[186:189], v[210:213], v[84:87]
	v_mfma_f32_16x16x32_bf16 v[84:87], v[190:193], v[214:217], v[84:87]
	v_mfma_f32_16x16x32_bf16 v[68:71], v[186:189], v[228:231], v[68:71]
	v_mfma_f32_16x16x32_bf16 v[68:71], v[190:193], v[232:235], v[68:71]
	v_mfma_f32_16x16x32_bf16 v[72:75], v[176:179], v[228:231], v[72:75]
	v_mfma_f32_16x16x32_bf16 v[72:75], v[182:185], v[232:235], v[72:75]
	s_waitcnt vmcnt(8)
	s_setprio 0
	s_barrier
.Ljoin_4:
	s_add_i32 s52, s52, s2
	v_lshl_add_u64 v[218:219], s[34:35], 0, v[150:151]
	s_mov_b32 m0, s52
	ds_read_b128 v[194:197], v181 offset:16384
	ds_read_b128 v[198:201], v181 offset:17408
	ds_read_b128 v[202:205], v181 offset:18432
	ds_read_b128 v[206:209], v181 offset:19456
	ds_read_b128 v[210:213], v181 offset:20480
	ds_read_b128 v[214:217], v181 offset:21504
	ds_read_b128 v[228:231], v181 offset:22528
	ds_read_b128 v[232:235], v181 offset:23552
	global_load_lds_dwordx4 v[218:219], off
	s_add_i32 m0, s52, 0x2000
	s_add_u32 s52, s34, 0x4000
	v_lshl_add_u64 v[218:219], s[34:35], 0, v[0:1]
	s_addc_u32 s53, s35, 0
	s_add_i32 s68, s68, s2
	global_load_lds_dwordx4 v[218:219], off
	v_lshl_add_u64 v[218:219], s[52:53], 0, v[150:151]
	s_mov_b32 m0, s68
	v_lshl_add_u64 v[236:237], s[46:47], 0, v[148:149]
	global_load_lds_dwordx4 v[218:219], off
	v_lshl_add_u64 v[218:219], s[52:53], 0, v[0:1]
	s_add_i32 m0, s68, 0x2000
	s_nop 0
	global_load_lds_dwordx4 v[218:219], off
	v_lshl_add_u64 v[218:219], s[46:47], 0, v[152:153]
	s_mov_b32 m0, s69
	s_nop 0
	global_load_lds_dwordx4 v[218:219], off
	s_mov_b32 m0, s71
	s_nop 0
	global_load_lds_dwordx4 v[236:237], off
	s_waitcnt lgkmcnt(0)
	s_cmp_eq_u32 s101, 0
	s_cbranch_scc1 .LtypeA_5
	s_waitcnt vmcnt(8)
	s_barrier
	s_setprio 2
	v_mfma_f32_16x16x32_bf16 v[64:67], v[132:135], v[194:197], v[64:67]
	v_mfma_f32_16x16x32_bf16 v[64:67], v[136:139], v[198:201], v[64:67]
	v_mfma_f32_16x16x32_bf16 v[60:63], v[140:143], v[194:197], v[60:63]
	v_mfma_f32_16x16x32_bf16 v[60:63], v[144:147], v[198:201], v[60:63]
	v_mfma_f32_16x16x32_bf16 v[44:47], v[140:143], v[202:205], v[44:47]
	v_mfma_f32_16x16x32_bf16 v[44:47], v[144:147], v[206:209], v[44:47]
	v_mfma_f32_16x16x32_bf16 v[48:51], v[132:135], v[202:205], v[48:51]
	v_mfma_f32_16x16x32_bf16 v[48:51], v[136:139], v[206:209], v[48:51]
	v_mfma_f32_16x16x32_bf16 v[32:35], v[132:135], v[210:213], v[32:35]
	v_mfma_f32_16x16x32_bf16 v[32:35], v[136:139], v[214:217], v[32:35]
	v_mfma_f32_16x16x32_bf16 v[28:31], v[140:143], v[210:213], v[28:31]
	v_mfma_f32_16x16x32_bf16 v[28:31], v[144:147], v[214:217], v[28:31]
	v_mfma_f32_16x16x32_bf16 v[12:15], v[140:143], v[228:231], v[12:15]
	v_mfma_f32_16x16x32_bf16 v[12:15], v[144:147], v[232:235], v[12:15]
	v_mfma_f32_16x16x32_bf16 v[16:19], v[132:135], v[228:231], v[16:19]
	v_mfma_f32_16x16x32_bf16 v[16:19], v[136:139], v[232:235], v[16:19]
	v_mfma_f32_16x16x32_bf16 v[56:59], v[176:179], v[194:197], v[56:59]
	v_mfma_f32_16x16x32_bf16 v[56:59], v[182:185], v[198:201], v[56:59]
	v_mfma_f32_16x16x32_bf16 v[52:55], v[186:189], v[194:197], v[52:55]
	v_mfma_f32_16x16x32_bf16 v[52:55], v[190:193], v[198:201], v[52:55]
	v_mfma_f32_16x16x32_bf16 v[36:39], v[186:189], v[202:205], v[36:39]
	v_mfma_f32_16x16x32_bf16 v[36:39], v[190:193], v[206:209], v[36:39]
	v_mfma_f32_16x16x32_bf16 v[40:43], v[176:179], v[202:205], v[40:43]
	v_mfma_f32_16x16x32_bf16 v[40:43], v[182:185], v[206:209], v[40:43]
	v_mfma_f32_16x16x32_bf16 v[24:27], v[176:179], v[210:213], v[24:27]
	v_mfma_f32_16x16x32_bf16 v[24:27], v[182:185], v[214:217], v[24:27]
	v_mfma_f32_16x16x32_bf16 v[20:23], v[186:189], v[210:213], v[20:23]
	v_mfma_f32_16x16x32_bf16 v[20:23], v[190:193], v[214:217], v[20:23]
	v_mfma_f32_16x16x32_bf16 v[4:7], v[186:189], v[228:231], v[4:7]
	v_mfma_f32_16x16x32_bf16 v[4:7], v[190:193], v[232:235], v[4:7]
	v_mfma_f32_16x16x32_bf16 v[8:11], v[176:179], v[228:231], v[8:11]
	v_mfma_f32_16x16x32_bf16 v[8:11], v[182:185], v[232:235], v[8:11]
	s_branch .Ljoin_5
.LtypeA_5:
	s_setprio 1
	v_mfma_f32_16x16x32_bf16 v[64:67], v[132:135], v[194:197], v[64:67]
	v_mfma_f32_16x16x32_bf16 v[64:67], v[136:139], v[198:201], v[64:67]
	v_mfma_f32_16x16x32_bf16 v[60:63], v[140:143], v[194:197], v[60:63]
	v_mfma_f32_16x16x32_bf16 v[60:63], v[144:147], v[198:201], v[60:63]
	v_mfma_f32_16x16x32_bf16 v[44:47], v[140:143], v[202:205], v[44:47]
	v_mfma_f32_16x16x32_bf16 v[44:47], v[144:147], v[206:209], v[44:47]
	v_mfma_f32_16x16x32_bf16 v[48:51], v[132:135], v[202:205], v[48:51]
	v_mfma_f32_16x16x32_bf16 v[48:51], v[136:139], v[206:209], v[48:51]
	v_mfma_f32_16x16x32_bf16 v[32:35], v[132:135], v[210:213], v[32:35]
	v_mfma_f32_16x16x32_bf16 v[32:35], v[136:139], v[214:217], v[32:35]
	v_mfma_f32_16x16x32_bf16 v[28:31], v[140:143], v[210:213], v[28:31]
	v_mfma_f32_16x16x32_bf16 v[28:31], v[144:147], v[214:217], v[28:31]
	v_mfma_f32_16x16x32_bf16 v[12:15], v[140:143], v[228:231], v[12:15]
	v_mfma_f32_16x16x32_bf16 v[12:15], v[144:147], v[232:235], v[12:15]
	v_mfma_f32_16x16x32_bf16 v[16:19], v[132:135], v[228:231], v[16:19]
	v_mfma_f32_16x16x32_bf16 v[16:19], v[136:139], v[232:235], v[16:19]
	v_mfma_f32_16x16x32_bf16 v[56:59], v[176:179], v[194:197], v[56:59]
	v_mfma_f32_16x16x32_bf16 v[56:59], v[182:185], v[198:201], v[56:59]
	v_mfma_f32_16x16x32_bf16 v[52:55], v[186:189], v[194:197], v[52:55]
	v_mfma_f32_16x16x32_bf16 v[52:55], v[190:193], v[198:201], v[52:55]
	v_mfma_f32_16x16x32_bf16 v[36:39], v[186:189], v[202:205], v[36:39]
	v_mfma_f32_16x16x32_bf16 v[36:39], v[190:193], v[206:209], v[36:39]
	v_mfma_f32_16x16x32_bf16 v[40:43], v[176:179], v[202:205], v[40:43]
	v_mfma_f32_16x16x32_bf16 v[40:43], v[182:185], v[206:209], v[40:43]
	v_mfma_f32_16x16x32_bf16 v[24:27], v[176:179], v[210:213], v[24:27]
	v_mfma_f32_16x16x32_bf16 v[24:27], v[182:185], v[214:217], v[24:27]
	v_mfma_f32_16x16x32_bf16 v[20:23], v[186:189], v[210:213], v[20:23]
	v_mfma_f32_16x16x32_bf16 v[20:23], v[190:193], v[214:217], v[20:23]
	v_mfma_f32_16x16x32_bf16 v[4:7], v[186:189], v[228:231], v[4:7]
	v_mfma_f32_16x16x32_bf16 v[4:7], v[190:193], v[232:235], v[4:7]
	v_mfma_f32_16x16x32_bf16 v[8:11], v[176:179], v[228:231], v[8:11]
	v_mfma_f32_16x16x32_bf16 v[8:11], v[182:185], v[232:235], v[8:11]
	s_waitcnt vmcnt(8)
	s_setprio 0
	s_barrier
.Ljoin_5:
	s_add_i32 s52, 0, 0x18000
	s_add_i32 s53, 0, 0x1c000
	v_add_u32_e32 v144, s52, v155
	v_add_u32_e32 v180, s53, v155
	ds_read_b128 v[132:135], v144
	ds_read_b128 v[136:139], v144 offset:1024
	ds_read_b128 v[140:143], v144 offset:2048
	ds_read_b128 v[144:147], v144 offset:3072
	ds_read_b128 v[176:179], v180
	ds_read_b128 v[182:185], v180 offset:1024
	ds_read_b128 v[186:189], v180 offset:2048
	ds_read_b128 v[190:193], v180 offset:3072
	s_add_u32 s46, s46, 0x80000
	s_addc_u32 s47, s47, 0
	s_mov_b32 m0, s88
	v_lshl_add_u64 v[238:239], s[46:47], 0, v[152:153]
	ds_read_b128 v[194:197], v181 offset:32768
	ds_read_b128 v[198:201], v181 offset:33792
	ds_read_b128 v[202:205], v181 offset:34816
	ds_read_b128 v[206:209], v181 offset:35840
	ds_read_b128 v[210:213], v181 offset:36864
	ds_read_b128 v[214:217], v181 offset:37888
	ds_read_b128 v[228:231], v181 offset:38912
	ds_read_b128 v[232:235], v181 offset:39936
	global_load_lds_dwordx4 v[238:239], off
	v_lshl_add_u64 v[238:239], s[46:47], 0, v[148:149]
	s_mov_b32 m0, s96
	s_nop 0
	global_load_lds_dwordx4 v[238:239], off
	s_waitcnt lgkmcnt(0)
	s_cmp_eq_u32 s101, 0
	s_cbranch_scc1 .LtypeA_6
	s_waitcnt vmcnt(8)
	s_barrier
	s_setprio 2
	v_mfma_f32_16x16x32_bf16 v[128:131], v[132:135], v[194:197], v[128:131]
	v_mfma_f32_16x16x32_bf16 v[128:131], v[136:139], v[198:201], v[128:131]
	v_mfma_f32_16x16x32_bf16 v[124:127], v[140:143], v[194:197], v[124:127]
	v_mfma_f32_16x16x32_bf16 v[124:127], v[144:147], v[198:201], v[124:127]
	v_mfma_f32_16x16x32_bf16 v[108:111], v[140:143], v[202:205], v[108:111]
	v_mfma_f32_16x16x32_bf16 v[108:111], v[144:147], v[206:209], v[108:111]
	v_mfma_f32_16x16x32_bf16 v[112:115], v[132:135], v[202:205], v[112:115]
	v_mfma_f32_16x16x32_bf16 v[112:115], v[136:139], v[206:209], v[112:115]
	v_mfma_f32_16x16x32_bf16 v[96:99], v[132:135], v[210:213], v[96:99]
	v_mfma_f32_16x16x32_bf16 v[96:99], v[136:139], v[214:217], v[96:99]
	v_mfma_f32_16x16x32_bf16 v[92:95], v[140:143], v[210:213], v[92:95]
	v_mfma_f32_16x16x32_bf16 v[92:95], v[144:147], v[214:217], v[92:95]
	v_mfma_f32_16x16x32_bf16 v[76:79], v[140:143], v[228:231], v[76:79]
	v_mfma_f32_16x16x32_bf16 v[76:79], v[144:147], v[232:235], v[76:79]
	v_mfma_f32_16x16x32_bf16 v[80:83], v[132:135], v[228:231], v[80:83]
	v_mfma_f32_16x16x32_bf16 v[80:83], v[136:139], v[232:235], v[80:83]
	v_mfma_f32_16x16x32_bf16 v[120:123], v[176:179], v[194:197], v[120:123]
	v_mfma_f32_16x16x32_bf16 v[120:123], v[182:185], v[198:201], v[120:123]
	v_mfma_f32_16x16x32_bf16 v[116:119], v[186:189], v[194:197], v[116:119]
	v_mfma_f32_16x16x32_bf16 v[116:119], v[190:193], v[198:201], v[116:119]
	v_mfma_f32_16x16x32_bf16 v[100:103], v[186:189], v[202:205], v[100:103]
	v_mfma_f32_16x16x32_bf16 v[100:103], v[190:193], v[206:209], v[100:103]
	v_mfma_f32_16x16x32_bf16 v[104:107], v[176:179], v[202:205], v[104:107]
	v_mfma_f32_16x16x32_bf16 v[104:107], v[182:185], v[206:209], v[104:107]
	v_mfma_f32_16x16x32_bf16 v[88:91], v[176:179], v[210:213], v[88:91]
	v_mfma_f32_16x16x32_bf16 v[88:91], v[182:185], v[214:217], v[88:91]
	v_mfma_f32_16x16x32_bf16 v[84:87], v[186:189], v[210:213], v[84:87]
	v_mfma_f32_16x16x32_bf16 v[84:87], v[190:193], v[214:217], v[84:87]
	v_mfma_f32_16x16x32_bf16 v[68:71], v[186:189], v[228:231], v[68:71]
	v_mfma_f32_16x16x32_bf16 v[68:71], v[190:193], v[232:235], v[68:71]
	v_mfma_f32_16x16x32_bf16 v[72:75], v[176:179], v[228:231], v[72:75]
	v_mfma_f32_16x16x32_bf16 v[72:75], v[182:185], v[232:235], v[72:75]
	s_branch .Ljoin_6

.Ljoin_6:
	s_add_u32 s46, s34, 0x70000
	s_addc_u32 s47, s35, 0
	s_add_i32 s52, s52, s2
	v_lshl_add_u64 v[238:239], s[46:47], 0, v[150:151]
	s_mov_b32 m0, s52
	ds_read_b128 v[194:197], v181 offset:49152
	ds_read_b128 v[198:201], v181 offset:50176
	ds_read_b128 v[202:205], v181 offset:51200
	ds_read_b128 v[206:209], v181 offset:52224
	ds_read_b128 v[210:213], v181 offset:53248
	ds_read_b128 v[214:217], v181 offset:54272
	ds_read_b128 v[228:231], v181 offset:55296
	ds_read_b128 v[232:235], v181 offset:56320
	global_load_lds_dwordx4 v[238:239], off
	s_add_i32 m0, s52, 0x2000
	s_add_u32 s34, s34, 0x74000
	v_lshl_add_u64 v[238:239], s[46:47], 0, v[0:1]
	s_addc_u32 s35, s35, 0
	s_add_i32 s46, s53, s2
	global_load_lds_dwordx4 v[238:239], off
	v_lshl_add_u64 v[238:239], s[34:35], 0, v[150:151]
	s_mov_b32 m0, s46
	v_lshl_add_u64 v[218:219], v[218:219], 0, s[14:15]
	global_load_lds_dwordx4 v[238:239], off
	v_lshl_add_u64 v[238:239], s[34:35], 0, v[0:1]
	s_add_i32 m0, s46, 0x2000
	s_nop 0
	global_load_lds_dwordx4 v[238:239], off
	s_mov_b32 m0, s97
	s_nop 0
	global_load_lds_dwordx4 v[218:219], off
	v_lshl_add_u64 v[218:219], v[236:237], 0, s[14:15]
	s_mov_b32 m0, s76
	s_nop 0
	global_load_lds_dwordx4 v[218:219], off
	s_waitcnt lgkmcnt(0)
	s_cmp_eq_u32 s101, 0
	s_cbranch_scc1 .LtypeA_7
	s_waitcnt vmcnt(8)
	s_barrier
	s_setprio 2
	v_mfma_f32_16x16x32_bf16 v[64:67], v[132:135], v[194:197], v[64:67]
	v_mfma_f32_16x16x32_bf16 v[64:67], v[136:139], v[198:201], v[64:67]
	v_mfma_f32_16x16x32_bf16 v[60:63], v[140:143], v[194:197], v[60:63]
	v_mfma_f32_16x16x32_bf16 v[60:63], v[144:147], v[198:201], v[60:63]
	v_mfma_f32_16x16x32_bf16 v[44:47], v[140:143], v[202:205], v[44:47]
	v_mfma_f32_16x16x32_bf16 v[44:47], v[144:147], v[206:209], v[44:47]
	v_mfma_f32_16x16x32_bf16 v[48:51], v[132:135], v[202:205], v[48:51]
	v_mfma_f32_16x16x32_bf16 v[48:51], v[136:139], v[206:209], v[48:51]
	v_mfma_f32_16x16x32_bf16 v[32:35], v[132:135], v[210:213], v[32:35]
	v_mfma_f32_16x16x32_bf16 v[32:35], v[136:139], v[214:217], v[32:35]
	v_mfma_f32_16x16x32_bf16 v[28:31], v[140:143], v[210:213], v[28:31]
	v_mfma_f32_16x16x32_bf16 v[28:31], v[144:147], v[214:217], v[28:31]
	v_mfma_f32_16x16x32_bf16 v[12:15], v[140:143], v[228:231], v[12:15]
	v_mfma_f32_16x16x32_bf16 v[12:15], v[144:147], v[232:235], v[12:15]
	v_mfma_f32_16x16x32_bf16 v[16:19], v[132:135], v[228:231], v[16:19]
	v_mfma_f32_16x16x32_bf16 v[16:19], v[136:139], v[232:235], v[16:19]
	v_mfma_f32_16x16x32_bf16 v[56:59], v[176:179], v[194:197], v[56:59]
	v_mfma_f32_16x16x32_bf16 v[56:59], v[182:185], v[198:201], v[56:59]
	v_mfma_f32_16x16x32_bf16 v[52:55], v[186:189], v[194:197], v[52:55]
	v_mfma_f32_16x16x32_bf16 v[52:55], v[190:193], v[198:201], v[52:55]
	v_mfma_f32_16x16x32_bf16 v[36:39], v[186:189], v[202:205], v[36:39]
	v_mfma_f32_16x16x32_bf16 v[36:39], v[190:193], v[206:209], v[36:39]
	v_mfma_f32_16x16x32_bf16 v[40:43], v[176:179], v[202:205], v[40:43]
	v_mfma_f32_16x16x32_bf16 v[40:43], v[182:185], v[206:209], v[40:43]
	v_mfma_f32_16x16x32_bf16 v[24:27], v[176:179], v[210:213], v[24:27]
	v_mfma_f32_16x16x32_bf16 v[24:27], v[182:185], v[214:217], v[24:27]
	v_mfma_f32_16x16x32_bf16 v[20:23], v[186:189], v[210:213], v[20:23]
	v_mfma_f32_16x16x32_bf16 v[20:23], v[190:193], v[214:217], v[20:23]
	v_mfma_f32_16x16x32_bf16 v[4:7], v[186:189], v[228:231], v[4:7]
	v_mfma_f32_16x16x32_bf16 v[4:7], v[190:193], v[232:235], v[4:7]
	v_mfma_f32_16x16x32_bf16 v[8:11], v[176:179], v[228:231], v[8:11]
	v_mfma_f32_16x16x32_bf16 v[8:11], v[182:185], v[232:235], v[8:11]
	s_branch .Ljoin_7

.LBB0_559:
	s_add_i32 vcc_lo, s34, 2
	s_add_u32 s35, s42, 0x80
	s_addc_u32 s52, s43, 0
	s_add_i32 s53, 0, 0x10000
	s_cmp_eq_u32 s77, s34
	s_cselect_b32 s57, s51, s52
	s_cselect_b32 s56, s50, s35
	s_cselect_b32 s35, s36, s97
	s_cselect_b32 s34, s37, s49
	s_add_i32 s68, 0, 0x14000
	v_add_u32_e32 v136, s53, v200
	v_add_u32_e32 v186, s68, v200
	ds_read_b128 v[116:119], v136
	ds_read_b128 v[120:123], v136 offset:1024
	ds_read_b128 v[124:127], v136 offset:2048
	ds_read_b128 v[136:139], v136 offset:3072
	ds_read_b128 v[148:151], v186
	ds_read_b128 v[152:155], v186 offset:1024
	ds_read_b128 v[182:185], v186 offset:2048
	ds_read_b128 v[186:189], v186 offset:3072
	v_lshl_add_u64 v[198:199], s[42:43], 0, v[178:179]
	s_add_i32 m0, s59, 0xc000
	ds_read_b128 v[190:193], v202
	ds_read_b128 v[194:197], v202 offset:1024
	ds_read_b128 v[204:207], v202 offset:2048
	ds_read_b128 v[208:211], v202 offset:3072
	ds_read_b128 v[212:215], v202 offset:4096
	ds_read_b128 v[216:219], v202 offset:5120
	ds_read_b128 v[228:231], v202 offset:6144
	ds_read_b128 v[232:235], v202 offset:7168
	global_load_lds_dwordx4 v[198:199], off
	v_lshl_add_u64 v[198:199], s[42:43], 0, v[180:181]
	s_add_i32 m0, s59, 0xe000
	s_nop 0
	global_load_lds_dwordx4 v[198:199], off
	s_waitcnt lgkmcnt(0)
	s_cmp_eq_u32 s101, 0
	s_cbranch_scc1 .LtypeA_8
	s_waitcnt vmcnt(8)
	s_barrier
	s_setprio 2
	v_mfma_f32_16x16x32_bf16 v[144:147], v[116:119], v[190:193], v[144:147]
	v_mfma_f32_16x16x32_bf16 v[144:147], v[120:123], v[194:197], v[144:147]
	v_mfma_f32_16x16x32_bf16 v[140:143], v[124:127], v[190:193], v[140:143]
	v_mfma_f32_16x16x32_bf16 v[140:143], v[136:139], v[194:197], v[140:143]
	v_mfma_f32_16x16x32_bf16 v[108:111], v[124:127], v[204:207], v[108:111]
	v_mfma_f32_16x16x32_bf16 v[108:111], v[136:139], v[208:211], v[108:111]
	v_mfma_f32_16x16x32_bf16 v[112:115], v[116:119], v[204:207], v[112:115]
	v_mfma_f32_16x16x32_bf16 v[112:115], v[120:123], v[208:211], v[112:115]
	v_mfma_f32_16x16x32_bf16 v[96:99], v[116:119], v[212:215], v[96:99]
	v_mfma_f32_16x16x32_bf16 v[96:99], v[120:123], v[216:219], v[96:99]
	v_mfma_f32_16x16x32_bf16 v[92:95], v[124:127], v[212:215], v[92:95]
	v_mfma_f32_16x16x32_bf16 v[92:95], v[136:139], v[216:219], v[92:95]
	v_mfma_f32_16x16x32_bf16 v[76:79], v[124:127], v[228:231], v[76:79]
	v_mfma_f32_16x16x32_bf16 v[76:79], v[136:139], v[232:235], v[76:79]
	v_mfma_f32_16x16x32_bf16 v[80:83], v[116:119], v[228:231], v[80:83]
	v_mfma_f32_16x16x32_bf16 v[80:83], v[120:123], v[232:235], v[80:83]
	v_mfma_f32_16x16x32_bf16 v[132:135], v[148:151], v[190:193], v[132:135]
	v_mfma_f32_16x16x32_bf16 v[132:135], v[152:155], v[194:197], v[132:135]
	v_mfma_f32_16x16x32_bf16 v[128:131], v[182:185], v[190:193], v[128:131]
	v_mfma_f32_16x16x32_bf16 v[128:131], v[186:189], v[194:197], v[128:131]
	v_mfma_f32_16x16x32_bf16 v[100:103], v[182:185], v[204:207], v[100:103]
	v_mfma_f32_16x16x32_bf16 v[100:103], v[186:189], v[208:211], v[100:103]
	v_mfma_f32_16x16x32_bf16 v[104:107], v[148:151], v[204:207], v[104:107]
	v_mfma_f32_16x16x32_bf16 v[104:107], v[152:155], v[208:211], v[104:107]
	v_mfma_f32_16x16x32_bf16 v[88:91], v[148:151], v[212:215], v[88:91]
	v_mfma_f32_16x16x32_bf16 v[88:91], v[152:155], v[216:219], v[88:91]
	v_mfma_f32_16x16x32_bf16 v[84:87], v[182:185], v[212:215], v[84:87]
	v_mfma_f32_16x16x32_bf16 v[84:87], v[186:189], v[216:219], v[84:87]
	v_mfma_f32_16x16x32_bf16 v[68:71], v[182:185], v[228:231], v[68:71]
	v_mfma_f32_16x16x32_bf16 v[68:71], v[186:189], v[232:235], v[68:71]
	v_mfma_f32_16x16x32_bf16 v[72:75], v[148:151], v[228:231], v[72:75]
	v_mfma_f32_16x16x32_bf16 v[72:75], v[152:155], v[232:235], v[72:75]
	s_branch .Ljoin_8
.LtypeA_8:
	s_setprio 1
	v_mfma_f32_16x16x32_bf16 v[144:147], v[116:119], v[190:193], v[144:147]
	v_mfma_f32_16x16x32_bf16 v[144:147], v[120:123], v[194:197], v[144:147]
	v_mfma_f32_16x16x32_bf16 v[140:143], v[124:127], v[190:193], v[140:143]
	v_mfma_f32_16x16x32_bf16 v[140:143], v[136:139], v[194:197], v[140:143]
	v_mfma_f32_16x16x32_bf16 v[108:111], v[124:127], v[204:207], v[108:111]
	v_mfma_f32_16x16x32_bf16 v[108:111], v[136:139], v[208:211], v[108:111]
	v_mfma_f32_16x16x32_bf16 v[112:115], v[116:119], v[204:207], v[112:115]
	v_mfma_f32_16x16x32_bf16 v[112:115], v[120:123], v[208:211], v[112:115]
	v_mfma_f32_16x16x32_bf16 v[96:99], v[116:119], v[212:215], v[96:99]
	v_mfma_f32_16x16x32_bf16 v[96:99], v[120:123], v[216:219], v[96:99]
	v_mfma_f32_16x16x32_bf16 v[92:95], v[124:127], v[212:215], v[92:95]
	v_mfma_f32_16x16x32_bf16 v[92:95], v[136:139], v[216:219], v[92:95]
	v_mfma_f32_16x16x32_bf16 v[76:79], v[124:127], v[228:231], v[76:79]
	v_mfma_f32_16x16x32_bf16 v[76:79], v[136:139], v[232:235], v[76:79]
	v_mfma_f32_16x16x32_bf16 v[80:83], v[116:119], v[228:231], v[80:83]
	v_mfma_f32_16x16x32_bf16 v[80:83], v[120:123], v[232:235], v[80:83]
	v_mfma_f32_16x16x32_bf16 v[132:135], v[148:151], v[190:193], v[132:135]
	v_mfma_f32_16x16x32_bf16 v[132:135], v[152:155], v[194:197], v[132:135]
	v_mfma_f32_16x16x32_bf16 v[128:131], v[182:185], v[190:193], v[128:131]
	v_mfma_f32_16x16x32_bf16 v[128:131], v[186:189], v[194:197], v[128:131]
	v_mfma_f32_16x16x32_bf16 v[100:103], v[182:185], v[204:207], v[100:103]
	v_mfma_f32_16x16x32_bf16 v[100:103], v[186:189], v[208:211], v[100:103]
	v_mfma_f32_16x16x32_bf16 v[104:107], v[148:151], v[204:207], v[104:107]
	v_mfma_f32_16x16x32_bf16 v[104:107], v[152:155], v[208:211], v[104:107]
	v_mfma_f32_16x16x32_bf16 v[88:91], v[148:151], v[212:215], v[88:91]
	v_mfma_f32_16x16x32_bf16 v[88:91], v[152:155], v[216:219], v[88:91]
	v_mfma_f32_16x16x32_bf16 v[84:87], v[182:185], v[212:215], v[84:87]
	v_mfma_f32_16x16x32_bf16 v[84:87], v[186:189], v[216:219], v[84:87]
	v_mfma_f32_16x16x32_bf16 v[68:71], v[182:185], v[228:231], v[68:71]
	v_mfma_f32_16x16x32_bf16 v[68:71], v[186:189], v[232:235], v[68:71]
	v_mfma_f32_16x16x32_bf16 v[72:75], v[148:151], v[228:231], v[72:75]
	v_mfma_f32_16x16x32_bf16 v[72:75], v[152:155], v[232:235], v[72:75]
	s_waitcnt vmcnt(8)
	s_setprio 0
	s_barrier
.Ljoin_8:
	s_add_i32 s52, s53, s58
	v_lshl_add_u64 v[198:199], s[34:35], 0, v[174:175]
	s_mov_b32 m0, s52
	ds_read_b128 v[190:193], v202 offset:16384
	ds_read_b128 v[194:197], v202 offset:17408
	ds_read_b128 v[204:207], v202 offset:18432
	ds_read_b128 v[208:211], v202 offset:19456
	ds_read_b128 v[212:215], v202 offset:20480
	ds_read_b128 v[216:219], v202 offset:21504
	ds_read_b128 v[228:231], v202 offset:22528
	ds_read_b128 v[232:235], v202 offset:23552
	global_load_lds_dwordx4 v[198:199], off
	s_add_i32 m0, s52, 0x2000
	s_add_u32 s52, s34, 0x4000
	v_lshl_add_u64 v[198:199], s[34:35], 0, v[0:1]
	s_addc_u32 s53, s35, 0
	s_add_i32 s68, s68, s58
	global_load_lds_dwordx4 v[198:199], off
	v_lshl_add_u64 v[198:199], s[52:53], 0, v[174:175]
	s_mov_b32 m0, s68
	v_lshl_add_u64 v[236:237], s[56:57], 0, v[172:173]
	global_load_lds_dwordx4 v[198:199], off
	v_lshl_add_u64 v[198:199], s[52:53], 0, v[0:1]
	s_add_i32 m0, s68, 0x2000
	s_nop 0
	global_load_lds_dwordx4 v[198:199], off
	v_lshl_add_u64 v[198:199], s[56:57], 0, v[176:177]
	s_mov_b32 m0, s59
	s_nop 0
	global_load_lds_dwordx4 v[198:199], off
	s_mov_b32 m0, s60
	s_nop 0
	global_load_lds_dwordx4 v[236:237], off
	s_waitcnt lgkmcnt(0)
	s_cmp_eq_u32 s101, 0
	s_cbranch_scc1 .LtypeA_9
	s_waitcnt vmcnt(8)
	s_barrier
	s_setprio 2
	v_mfma_f32_16x16x32_bf16 v[64:67], v[116:119], v[190:193], v[64:67]
	v_mfma_f32_16x16x32_bf16 v[64:67], v[120:123], v[194:197], v[64:67]
	v_mfma_f32_16x16x32_bf16 v[60:63], v[124:127], v[190:193], v[60:63]
	v_mfma_f32_16x16x32_bf16 v[60:63], v[136:139], v[194:197], v[60:63]
	v_mfma_f32_16x16x32_bf16 v[44:47], v[124:127], v[204:207], v[44:47]
	v_mfma_f32_16x16x32_bf16 v[44:47], v[136:139], v[208:211], v[44:47]
	v_mfma_f32_16x16x32_bf16 v[48:51], v[116:119], v[204:207], v[48:51]
	v_mfma_f32_16x16x32_bf16 v[48:51], v[120:123], v[208:211], v[48:51]
	v_mfma_f32_16x16x32_bf16 v[32:35], v[116:119], v[212:215], v[32:35]
	v_mfma_f32_16x16x32_bf16 v[32:35], v[120:123], v[216:219], v[32:35]
	v_mfma_f32_16x16x32_bf16 v[28:31], v[124:127], v[212:215], v[28:31]
	v_mfma_f32_16x16x32_bf16 v[28:31], v[136:139], v[216:219], v[28:31]
	v_mfma_f32_16x16x32_bf16 v[12:15], v[124:127], v[228:231], v[12:15]
	v_mfma_f32_16x16x32_bf16 v[12:15], v[136:139], v[232:235], v[12:15]
	v_mfma_f32_16x16x32_bf16 v[16:19], v[116:119], v[228:231], v[16:19]
	v_mfma_f32_16x16x32_bf16 v[16:19], v[120:123], v[232:235], v[16:19]
	v_mfma_f32_16x16x32_bf16 v[56:59], v[148:151], v[190:193], v[56:59]
	v_mfma_f32_16x16x32_bf16 v[56:59], v[152:155], v[194:197], v[56:59]
	v_mfma_f32_16x16x32_bf16 v[52:55], v[182:185], v[190:193], v[52:55]
	v_mfma_f32_16x16x32_bf16 v[52:55], v[186:189], v[194:197], v[52:55]
	v_mfma_f32_16x16x32_bf16 v[36:39], v[182:185], v[204:207], v[36:39]
	v_mfma_f32_16x16x32_bf16 v[36:39], v[186:189], v[208:211], v[36:39]
	v_mfma_f32_16x16x32_bf16 v[40:43], v[148:151], v[204:207], v[40:43]
	v_mfma_f32_16x16x32_bf16 v[40:43], v[152:155], v[208:211], v[40:43]
	v_mfma_f32_16x16x32_bf16 v[24:27], v[148:151], v[212:215], v[24:27]
	v_mfma_f32_16x16x32_bf16 v[24:27], v[152:155], v[216:219], v[24:27]
	v_mfma_f32_16x16x32_bf16 v[20:23], v[182:185], v[212:215], v[20:23]
	v_mfma_f32_16x16x32_bf16 v[20:23], v[186:189], v[216:219], v[20:23]
	v_mfma_f32_16x16x32_bf16 v[4:7], v[182:185], v[228:231], v[4:7]
	v_mfma_f32_16x16x32_bf16 v[4:7], v[186:189], v[232:235], v[4:7]
	v_mfma_f32_16x16x32_bf16 v[8:11], v[148:151], v[228:231], v[8:11]
	v_mfma_f32_16x16x32_bf16 v[8:11], v[152:155], v[232:235], v[8:11]
	s_branch .Ljoin_9
.LtypeA_9:
	s_setprio 1
	v_mfma_f32_16x16x32_bf16 v[64:67], v[116:119], v[190:193], v[64:67]
	v_mfma_f32_16x16x32_bf16 v[64:67], v[120:123], v[194:197], v[64:67]
	v_mfma_f32_16x16x32_bf16 v[60:63], v[124:127], v[190:193], v[60:63]
	v_mfma_f32_16x16x32_bf16 v[60:63], v[136:139], v[194:197], v[60:63]
	v_mfma_f32_16x16x32_bf16 v[44:47], v[124:127], v[204:207], v[44:47]
	v_mfma_f32_16x16x32_bf16 v[44:47], v[136:139], v[208:211], v[44:47]
	v_mfma_f32_16x16x32_bf16 v[48:51], v[116:119], v[204:207], v[48:51]
	v_mfma_f32_16x16x32_bf16 v[48:51], v[120:123], v[208:211], v[48:51]
	v_mfma_f32_16x16x32_bf16 v[32:35], v[116:119], v[212:215], v[32:35]
	v_mfma_f32_16x16x32_bf16 v[32:35], v[120:123], v[216:219], v[32:35]
	v_mfma_f32_16x16x32_bf16 v[28:31], v[124:127], v[212:215], v[28:31]
	v_mfma_f32_16x16x32_bf16 v[28:31], v[136:139], v[216:219], v[28:31]
	v_mfma_f32_16x16x32_bf16 v[12:15], v[124:127], v[228:231], v[12:15]
	v_mfma_f32_16x16x32_bf16 v[12:15], v[136:139], v[232:235], v[12:15]
	v_mfma_f32_16x16x32_bf16 v[16:19], v[116:119], v[228:231], v[16:19]
	v_mfma_f32_16x16x32_bf16 v[16:19], v[120:123], v[232:235], v[16:19]
	v_mfma_f32_16x16x32_bf16 v[56:59], v[148:151], v[190:193], v[56:59]
	v_mfma_f32_16x16x32_bf16 v[56:59], v[152:155], v[194:197], v[56:59]
	v_mfma_f32_16x16x32_bf16 v[52:55], v[182:185], v[190:193], v[52:55]
	v_mfma_f32_16x16x32_bf16 v[52:55], v[186:189], v[194:197], v[52:55]
	v_mfma_f32_16x16x32_bf16 v[36:39], v[182:185], v[204:207], v[36:39]
	v_mfma_f32_16x16x32_bf16 v[36:39], v[186:189], v[208:211], v[36:39]
	v_mfma_f32_16x16x32_bf16 v[40:43], v[148:151], v[204:207], v[40:43]
	v_mfma_f32_16x16x32_bf16 v[40:43], v[152:155], v[208:211], v[40:43]
	v_mfma_f32_16x16x32_bf16 v[24:27], v[148:151], v[212:215], v[24:27]
	v_mfma_f32_16x16x32_bf16 v[24:27], v[152:155], v[216:219], v[24:27]
	v_mfma_f32_16x16x32_bf16 v[20:23], v[182:185], v[212:215], v[20:23]
	v_mfma_f32_16x16x32_bf16 v[20:23], v[186:189], v[216:219], v[20:23]
	v_mfma_f32_16x16x32_bf16 v[4:7], v[182:185], v[228:231], v[4:7]
	v_mfma_f32_16x16x32_bf16 v[4:7], v[186:189], v[232:235], v[4:7]
	v_mfma_f32_16x16x32_bf16 v[8:11], v[148:151], v[228:231], v[8:11]
	v_mfma_f32_16x16x32_bf16 v[8:11], v[152:155], v[232:235], v[8:11]
	s_waitcnt vmcnt(8)
	s_setprio 0
	s_barrier
.Ljoin_9:
	s_add_i32 s68, 0, 0x18000
	s_add_i32 vcc_hi, 0, 0x1c000
	v_add_u32_e32 v136, s68, v200
	v_add_u32_e32 v186, vcc_hi, v200
	ds_read_b128 v[116:119], v136
	ds_read_b128 v[120:123], v136 offset:1024
	ds_read_b128 v[124:127], v136 offset:2048
	ds_read_b128 v[136:139], v136 offset:3072
	ds_read_b128 v[148:151], v186
	ds_read_b128 v[152:155], v186 offset:1024
	ds_read_b128 v[182:185], v186 offset:2048
	ds_read_b128 v[186:189], v186 offset:3072
	s_add_u32 s52, s56, s26
	s_addc_u32 s53, s57, 0
	s_mov_b32 m0, s61
	v_lshl_add_u64 v[238:239], s[52:53], 0, v[176:177]
	ds_read_b128 v[190:193], v202 offset:32768
	ds_read_b128 v[194:197], v202 offset:33792
	ds_read_b128 v[204:207], v202 offset:34816
	ds_read_b128 v[208:211], v202 offset:35840
	ds_read_b128 v[212:215], v202 offset:36864
	ds_read_b128 v[216:219], v202 offset:37888
	ds_read_b128 v[228:231], v202 offset:38912
	ds_read_b128 v[232:235], v202 offset:39936
	global_load_lds_dwordx4 v[238:239], off
	v_lshl_add_u64 v[238:239], s[52:53], 0, v[172:173]
	s_mov_b32 m0, s62
	s_nop 0
	global_load_lds_dwordx4 v[238:239], off
	s_waitcnt lgkmcnt(0)
	s_cmp_eq_u32 s101, 0
	s_cbranch_scc1 .LtypeA_10
	s_waitcnt vmcnt(8)
	s_barrier
	s_setprio 2
	v_mfma_f32_16x16x32_bf16 v[144:147], v[116:119], v[190:193], v[144:147]
	v_mfma_f32_16x16x32_bf16 v[144:147], v[120:123], v[194:197], v[144:147]
	v_mfma_f32_16x16x32_bf16 v[140:143], v[124:127], v[190:193], v[140:143]
	v_mfma_f32_16x16x32_bf16 v[140:143], v[136:139], v[194:197], v[140:143]
	v_mfma_f32_16x16x32_bf16 v[108:111], v[124:127], v[204:207], v[108:111]
	v_mfma_f32_16x16x32_bf16 v[108:111], v[136:139], v[208:211], v[108:111]
	v_mfma_f32_16x16x32_bf16 v[112:115], v[116:119], v[204:207], v[112:115]
	v_mfma_f32_16x16x32_bf16 v[112:115], v[120:123], v[208:211], v[112:115]
	v_mfma_f32_16x16x32_bf16 v[96:99], v[116:119], v[212:215], v[96:99]
	v_mfma_f32_16x16x32_bf16 v[96:99], v[120:123], v[216:219], v[96:99]
	v_mfma_f32_16x16x32_bf16 v[92:95], v[124:127], v[212:215], v[92:95]
	v_mfma_f32_16x16x32_bf16 v[92:95], v[136:139], v[216:219], v[92:95]
	v_mfma_f32_16x16x32_bf16 v[76:79], v[124:127], v[228:231], v[76:79]
	v_mfma_f32_16x16x32_bf16 v[76:79], v[136:139], v[232:235], v[76:79]
	v_mfma_f32_16x16x32_bf16 v[80:83], v[116:119], v[228:231], v[80:83]
	v_mfma_f32_16x16x32_bf16 v[80:83], v[120:123], v[232:235], v[80:83]
	v_mfma_f32_16x16x32_bf16 v[132:135], v[148:151], v[190:193], v[132:135]
	v_mfma_f32_16x16x32_bf16 v[132:135], v[152:155], v[194:197], v[132:135]
	v_mfma_f32_16x16x32_bf16 v[128:131], v[182:185], v[190:193], v[128:131]
	v_mfma_f32_16x16x32_bf16 v[128:131], v[186:189], v[194:197], v[128:131]
	v_mfma_f32_16x16x32_bf16 v[100:103], v[182:185], v[204:207], v[100:103]
	v_mfma_f32_16x16x32_bf16 v[100:103], v[186:189], v[208:211], v[100:103]
	v_mfma_f32_16x16x32_bf16 v[104:107], v[148:151], v[204:207], v[104:107]
	v_mfma_f32_16x16x32_bf16 v[104:107], v[152:155], v[208:211], v[104:107]
	v_mfma_f32_16x16x32_bf16 v[88:91], v[148:151], v[212:215], v[88:91]
	v_mfma_f32_16x16x32_bf16 v[88:91], v[152:155], v[216:219], v[88:91]
	v_mfma_f32_16x16x32_bf16 v[84:87], v[182:185], v[212:215], v[84:87]
	v_mfma_f32_16x16x32_bf16 v[84:87], v[186:189], v[216:219], v[84:87]
	v_mfma_f32_16x16x32_bf16 v[68:71], v[182:185], v[228:231], v[68:71]
	v_mfma_f32_16x16x32_bf16 v[68:71], v[186:189], v[232:235], v[68:71]
	v_mfma_f32_16x16x32_bf16 v[72:75], v[148:151], v[228:231], v[72:75]
	v_mfma_f32_16x16x32_bf16 v[72:75], v[152:155], v[232:235], v[72:75]
	s_branch .Ljoin_10

.Ljoin_10:
	s_add_u32 s52, s34, 0x40000
	s_addc_u32 s53, s35, 0
	s_add_i32 s56, s68, s58
	v_lshl_add_u64 v[238:239], s[52:53], 0, v[174:175]
	s_mov_b32 m0, s56
	ds_read_b128 v[190:193], v202 offset:49152
	ds_read_b128 v[194:197], v202 offset:50176
	ds_read_b128 v[204:207], v202 offset:51200
	ds_read_b128 v[208:211], v202 offset:52224
	ds_read_b128 v[212:215], v202 offset:53248
	ds_read_b128 v[216:219], v202 offset:54272
	ds_read_b128 v[228:231], v202 offset:55296
	ds_read_b128 v[232:235], v202 offset:56320
	global_load_lds_dwordx4 v[238:239], off
	s_add_i32 m0, s56, 0x2000
	s_add_u32 s34, s34, 0x44000
	v_lshl_add_u64 v[238:239], s[52:53], 0, v[0:1]
	s_addc_u32 s35, s35, 0
	s_add_i32 s52, vcc_hi, s58
	global_load_lds_dwordx4 v[238:239], off
	v_lshl_add_u64 v[238:239], s[34:35], 0, v[174:175]
	s_mov_b32 m0, s52
	v_lshl_add_u64 v[198:199], v[198:199], 0, s[14:15]
	global_load_lds_dwordx4 v[238:239], off
	v_lshl_add_u64 v[238:239], s[34:35], 0, v[0:1]
	s_add_i32 m0, s52, 0x2000
	s_nop 0
	global_load_lds_dwordx4 v[238:239], off
	s_mov_b32 m0, s71
	s_nop 0
	global_load_lds_dwordx4 v[198:199], off
	v_lshl_add_u64 v[198:199], v[236:237], 0, s[14:15]
	s_mov_b32 m0, s76
	s_nop 0
	global_load_lds_dwordx4 v[198:199], off
	s_waitcnt lgkmcnt(0)
	s_cmp_eq_u32 s101, 0
	s_cbranch_scc1 .LtypeA_11
	s_waitcnt vmcnt(8)
	s_barrier
	s_setprio 2
	v_mfma_f32_16x16x32_bf16 v[64:67], v[116:119], v[190:193], v[64:67]
	v_mfma_f32_16x16x32_bf16 v[64:67], v[120:123], v[194:197], v[64:67]
	v_mfma_f32_16x16x32_bf16 v[60:63], v[124:127], v[190:193], v[60:63]
	v_mfma_f32_16x16x32_bf16 v[60:63], v[136:139], v[194:197], v[60:63]
	v_mfma_f32_16x16x32_bf16 v[44:47], v[124:127], v[204:207], v[44:47]
	v_mfma_f32_16x16x32_bf16 v[44:47], v[136:139], v[208:211], v[44:47]
	v_mfma_f32_16x16x32_bf16 v[48:51], v[116:119], v[204:207], v[48:51]
	v_mfma_f32_16x16x32_bf16 v[48:51], v[120:123], v[208:211], v[48:51]
	v_mfma_f32_16x16x32_bf16 v[32:35], v[116:119], v[212:215], v[32:35]
	v_mfma_f32_16x16x32_bf16 v[32:35], v[120:123], v[216:219], v[32:35]
	v_mfma_f32_16x16x32_bf16 v[28:31], v[124:127], v[212:215], v[28:31]
	v_mfma_f32_16x16x32_bf16 v[28:31], v[136:139], v[216:219], v[28:31]
	v_mfma_f32_16x16x32_bf16 v[12:15], v[124:127], v[228:231], v[12:15]
	v_mfma_f32_16x16x32_bf16 v[12:15], v[136:139], v[232:235], v[12:15]
	v_mfma_f32_16x16x32_bf16 v[16:19], v[116:119], v[228:231], v[16:19]
	v_mfma_f32_16x16x32_bf16 v[16:19], v[120:123], v[232:235], v[16:19]
	v_mfma_f32_16x16x32_bf16 v[56:59], v[148:151], v[190:193], v[56:59]
	v_mfma_f32_16x16x32_bf16 v[56:59], v[152:155], v[194:197], v[56:59]
	v_mfma_f32_16x16x32_bf16 v[52:55], v[182:185], v[190:193], v[52:55]
	v_mfma_f32_16x16x32_bf16 v[52:55], v[186:189], v[194:197], v[52:55]
	v_mfma_f32_16x16x32_bf16 v[36:39], v[182:185], v[204:207], v[36:39]
	v_mfma_f32_16x16x32_bf16 v[36:39], v[186:189], v[208:211], v[36:39]
	v_mfma_f32_16x16x32_bf16 v[40:43], v[148:151], v[204:207], v[40:43]
	v_mfma_f32_16x16x32_bf16 v[40:43], v[152:155], v[208:211], v[40:43]
	v_mfma_f32_16x16x32_bf16 v[24:27], v[148:151], v[212:215], v[24:27]
	v_mfma_f32_16x16x32_bf16 v[24:27], v[152:155], v[216:219], v[24:27]
	v_mfma_f32_16x16x32_bf16 v[20:23], v[182:185], v[212:215], v[20:23]
	v_mfma_f32_16x16x32_bf16 v[20:23], v[186:189], v[216:219], v[20:23]
	v_mfma_f32_16x16x32_bf16 v[4:7], v[182:185], v[228:231], v[4:7]
	v_mfma_f32_16x16x32_bf16 v[4:7], v[186:189], v[232:235], v[4:7]
	v_mfma_f32_16x16x32_bf16 v[8:11], v[148:151], v[228:231], v[8:11]
	v_mfma_f32_16x16x32_bf16 v[8:11], v[152:155], v[232:235], v[8:11]
	s_branch .Ljoin_11
